# P10: ln1 gain/bias + adaLN shift2/scale2 staged once in LDS (64 global reloads per 4 rows -> ds_read_b128), all loop waits re-derived so h2 stores are no longer drained
# speedup vs baseline: 1.0054x; 1.0054x over previous
; DI void row_stats(const float (&v)[16], float& mean, float& rstd) {
;     float s = 0.f;
; #pragma unroll
;     for (int i = 0; i < 16; ++i) s += v[i];
;     mean = wsum(s) * (1.f / 1024.f);
;     float q = 0.f;
; #pragma unroll
;     for (int i = 0; i < 16; ++i) { float d = v[i] - mean; q += d * d; }
;     rstd = rsqrtf(wsum(q) * (1.f / 1024.f) + 1e-5f);
; DI void phase10(const Params& p) {
;     ...
;             for (int i = 0; i < 4; ++i) {
;                 int c = i * 256 + lane * 4;
;                 float4 g = *(const float4*)(p.in[22] + c), bb = *(const float4*)(p.in[23] + c);
;                 v[rr][4 * i] = (v[rr][4 * i] - mean) * rstd * g.x + bb.x;
;                 v[rr][4 * i + 1] = (v[rr][4 * i + 1] - mean) * rstd * g.y + bb.y;
;                 v[rr][4 * i + 2] = (v[rr][4 * i + 2] - mean) * rstd * g.z + bb.z;
;                 v[rr][4 * i + 3] = (v[rr][4 * i + 3] - mean) * rstd * g.w + bb.w;
;             }
;             row_stats(v[rr], mean, rstd);
.LBB0_987:
	s_or_b64 exec, exec, s[4:5]
	v_mov_b32_e32 v0, v250
	s_waitcnt lgkmcnt(0)
	s_barrier
	v_readlane_b32 s84, v254, 32
	v_readlane_b32 s85, v254, 33
	v_readlane_b32 s86, v254, 34
	v_readlane_b32 s87, v254, 35
	v_lshlrev_b32_e32 v200, 4, v250
	v_and_b32_e32 v201, 0xff0, v200
	v_add_u32_e32 v202, 0x3000, v200
	v_add_u32_e32 v203, 0x9000, v200
	v_add_u32_e32 v204, 0xf000, v200
	v_add_u32_e32 v205, 0x15000, v200
	global_load_dwordx4 v[208:211], v201, s[84:85]
	global_load_dwordx4 v[212:215], v201, s[86:87]
	global_load_dwordx4 v[216:219], v202, s[50:51]
	global_load_dwordx4 v[220:223], v203, s[50:51]
	global_load_dwordx4 v[224:227], v204, s[50:51]
	global_load_dwordx4 v[228:231], v205, s[50:51]
	s_waitcnt vmcnt(0)
	ds_write_b128 v201, v[208:211] offset:1024
	ds_write_b128 v201, v[212:215] offset:5120
	ds_write_b128 v200, v[216:219] offset:9216
	ds_write_b128 v200, v[220:223] offset:17408
	ds_write_b128 v200, v[224:227] offset:25600
	ds_write_b128 v200, v[228:231] offset:33792
	s_waitcnt lgkmcnt(0)
	s_barrier
	v_readlane_b32 s3, v254, 52
	v_ashrrev_i32_e32 v1, 4, v0
	v_and_b32_e32 v1, -4, v1
	s_add_u32 s10, s70, 0x34e6100
	v_add_u32_e32 v4, s3, v1
	s_mov_b32 s3, 0x8000
	s_addc_u32 s11, s71, 0
	v_cmp_gt_i32_e32 vcc, s3, v4
	s_and_saveexec_b64 s[6:7], vcc
	s_cbranch_execz .LBB0_998
	v_readlane_b32 s12, v254, 20
	v_and_b32_e32 v1, 63, v0
	v_readlane_b32 s13, v254, 21
	v_readlane_b32 s14, v254, 22
	v_readlane_b32 s15, v254, 23
	v_readlane_b32 s24, v254, 32
	v_readlane_b32 s25, v254, 33
	v_lshlrev_b32_e32 v0, 2, v1
	v_mov_b32_e32 v7, 0
	v_readlane_b32 s4, v254, 56
	v_readlane_b32 s26, v254, 34
	v_readlane_b32 s27, v254, 35
	s_mov_b64 s[12:13], s[24:25]
	v_lshlrev_b32_e32 v6, 3, v1
	v_readlane_b32 s5, v254, 57
	v_or_b32_e32 v2, 0x100, v0
	v_or_b32_e32 v20, 0x200, v0
	v_or_b32_e32 v22, 0x300, v0
	v_lshlrev_b32_e32 v12, 4, v1
	v_mov_b32_e32 v13, v7
	v_readlane_b32 s16, v254, 24
	v_readlane_b32 s17, v254, 25
	v_readlane_b32 s18, v254, 26
	s_mov_b64 s[14:15], s[26:27]
	v_lshl_add_u64 v[8:9], s[4:5], 0, v[6:7]
	v_cmp_eq_u32_e32 vcc, 0, v1
	s_lshl_b32 s3, s33, 5
	v_lshl_add_u64 v[10:11], s[12:13], 0, v[12:13]
	v_lshl_add_u64 v[12:13], s[14:15], 0, v[12:13]
	v_lshl_add_u64 v[14:15], s[96:97], 0, v[6:7]
	s_mov_b64 s[8:9], 0
	s_mov_b32 s12, 0x3a800000
	v_mov_b32_e32 v16, 0x3727c5ac
	s_mov_b32 s13, 0x800000
	s_mov_b64 s[14:15], 0x3000
	s_mov_b64 s[16:17], 0x4000
	v_lshlrev_b32_e32 v6, 2, v0
	v_lshlrev_b32_e32 v18, 2, v2
	v_lshlrev_b32_e32 v20, 2, v20
	v_lshlrev_b32_e32 v22, 2, v22
	s_movk_i32 s18, 0x7fff
	v_readlane_b32 s19, v254, 27
	v_readlane_b32 s20, v254, 28
	v_readlane_b32 s21, v254, 29
	v_readlane_b32 s22, v254, 30
	v_readlane_b32 s23, v254, 31
	s_branch .LBB0_990
.LBB0_989:
	s_or_b64 exec, exec, s[4:5]
	ds_read_b128 v[58:61], v6 offset:4096
	ds_read_b128 v[62:65], v6 offset:8192
	ds_read_b128 v[66:69], v6 offset:5120
	ds_read_b128 v[70:73], v6 offset:1024
	ds_read_b128 v[74:77], v6 offset:2048
	ds_read_b128 v[78:81], v6 offset:6144
	ds_read_b128 v[82:85], v6 offset:3072
	ds_read_b128 v[86:89], v6 offset:7168
	v_pk_mul_f32 v[90:91], v[36:37], v[28:29] op_sel_hi:[1,0]
	v_pk_mul_f32 v[92:93], v[38:39], v[28:29] op_sel_hi:[1,0]
	v_pk_mul_f32 v[44:45], v[44:45], v[28:29] op_sel_hi:[1,0]
	v_pk_mul_f32 v[48:49], v[48:49], v[28:29] op_sel_hi:[1,0]
	v_pk_mul_f32 v[50:51], v[50:51], v[28:29] op_sel_hi:[1,0]
	v_pk_mul_f32 v[52:53], v[52:53], v[28:29] op_sel_hi:[1,0]
	v_pk_mul_f32 v[54:55], v[54:55], v[28:29] op_sel_hi:[1,0]
	v_pk_mul_f32 v[56:57], v[56:57], v[28:29] op_sel_hi:[1,0]
	ds_read_b128 v[26:29], v140 offset:9216
	ds_read_b128 v[36:39], v140 offset:13312
	v_add_u32_e32 v4, s3, v4
	s_waitcnt vmcnt(13) lgkmcnt(8)
	v_pk_fma_f32 v[30:31], v[56:57], v[60:61], v[64:65]
	v_pk_fma_f32 v[54:55], v[54:55], v[58:59], v[62:63]
	s_waitcnt vmcnt(13) lgkmcnt(6)
	v_pk_fma_f32 v[56:57], v[90:91], v[70:71], v[66:67]
	v_pk_fma_f32 v[32:33], v[92:93], v[72:73], v[68:69]
	v_add_f32_e32 v5, 0, v56
	v_add_f32_e32 v5, v5, v57
	v_add_f32_e32 v5, v5, v32
	s_waitcnt vmcnt(13) lgkmcnt(4)
	v_pk_fma_f32 v[44:45], v[44:45], v[74:75], v[78:79]
	v_add_f32_e32 v5, v5, v33
	v_add_f32_e32 v5, v5, v44
	v_pk_fma_f32 v[48:49], v[48:49], v[76:77], v[80:81]
	v_add_f32_e32 v5, v5, v45
	v_add_f32_e32 v5, v5, v48
	s_waitcnt vmcnt(13) lgkmcnt(2)
	v_pk_fma_f32 v[50:51], v[50:51], v[82:83], v[86:87]
	v_add_f32_e32 v5, v5, v49
	v_add_f32_e32 v5, v5, v50
	v_pk_fma_f32 v[52:53], v[52:53], v[84:85], v[88:89]
	v_add_f32_e32 v5, v5, v51
	v_add_f32_e32 v5, v5, v52
	v_add_f32_e32 v5, v5, v53
	v_add_f32_e32 v5, v5, v54
	v_add_f32_e32 v5, v5, v55
	v_add_f32_e32 v5, v5, v30
	v_add_f32_e32 v5, v5, v31
	s_nop 1
	v_add_f32_dpp v5, v5, v5 quad_perm:[1,0,3,2] row_mask:0xf bank_mask:0xf bound_ctrl:1
	s_nop 1
	v_add_f32_dpp v5, v5, v5 quad_perm:[2,3,0,1] row_mask:0xf bank_mask:0xf bound_ctrl:1
	s_nop 1
	v_add_f32_dpp v5, v5, v5 row_half_mirror row_mask:0xf bank_mask:0xf bound_ctrl:1
	s_nop 1
	v_add_f32_dpp v5, v5, v5 row_mirror row_mask:0xf bank_mask:0xf bound_ctrl:1
	s_nop 0
	v_readlane_b32 s5, v5, 16
	v_readlane_b32 s4, v5, 0
	v_readlane_b32 s19, v5, 32
	v_readlane_b32 s20, v5, 48
	v_mov_b32_e32 v5, s5
	v_add_f32_e32 v5, s4, v5
	v_add_f32_e32 v5, s19, v5
	v_add_f32_e32 v5, s20, v5
	v_mul_f32_e32 v58, 0x3a800000, v5
	v_pk_add_f32 v[56:57], v[56:57], v[58:59] op_sel_hi:[1,0] neg_lo:[0,1] neg_hi:[0,1]
	v_pk_add_f32 v[32:33], v[32:33], v[58:59] op_sel_hi:[1,0] neg_lo:[0,1] neg_hi:[0,1]
	v_pk_add_f32 v[44:45], v[44:45], v[58:59] op_sel_hi:[1,0] neg_lo:[0,1] neg_hi:[0,1]
	v_pk_add_f32 v[48:49], v[48:49], v[58:59] op_sel_hi:[1,0] neg_lo:[0,1] neg_hi:[0,1]
	v_pk_add_f32 v[50:51], v[50:51], v[58:59] op_sel_hi:[1,0] neg_lo:[0,1] neg_hi:[0,1]
	v_pk_add_f32 v[52:53], v[52:53], v[58:59] op_sel_hi:[1,0] neg_lo:[0,1] neg_hi:[0,1]
	v_pk_add_f32 v[54:55], v[54:55], v[58:59] op_sel_hi:[1,0] neg_lo:[0,1] neg_hi:[0,1]
	v_pk_add_f32 v[58:59], v[30:31], v[58:59] op_sel_hi:[1,0] neg_lo:[0,1] neg_hi:[0,1]
	v_pk_mul_f32 v[30:31], v[56:57], v[56:57]
	v_pk_mul_f32 v[60:61], v[32:33], v[32:33]
	v_add_f32_e32 v5, v30, v31
	v_add_f32_e32 v5, v60, v5
	v_pk_mul_f32 v[62:63], v[44:45], v[44:45]
	v_add_f32_e32 v5, v61, v5
	v_add_f32_e32 v5, v62, v5
	v_pk_mul_f32 v[64:65], v[48:49], v[48:49]
	v_add_f32_e32 v5, v63, v5
	v_add_f32_e32 v5, v64, v5
	v_pk_mul_f32 v[66:67], v[50:51], v[50:51]
	v_add_f32_e32 v5, v65, v5
	v_add_f32_e32 v5, v66, v5
	v_pk_mul_f32 v[68:69], v[52:53], v[52:53]
	v_add_f32_e32 v5, v67, v5
	v_add_f32_e32 v5, v68, v5
	v_pk_mul_f32 v[70:71], v[54:55], v[54:55]
	v_add_f32_e32 v5, v69, v5
	v_add_f32_e32 v5, v70, v5
	v_pk_mul_f32 v[72:73], v[58:59], v[58:59]
	v_add_f32_e32 v5, v71, v5
	v_add_f32_e32 v5, v72, v5
	v_add_f32_e32 v5, v73, v5
	v_lshl_add_u64 v[60:61], v[14:15], 0, v[24:25]
	s_waitcnt vmcnt(13) lgkmcnt(0)
; DI float bf2f(unsigned short h) { return __uint_as_float(((unsigned)h) << 16); }
; DI uint2 pk4(f32x4 v) { return make_uint2(pk2(v[0], v[1]), pk2(v[2], v[3])); }
; DI void phase10(const Params& p) {
;     ...
; #pragma unroll
;         for (int rr = 0; rr < 4; ++rr)
; #pragma unroll
;             for (int i = 0; i < 4; ++i) { uint2 t = *(const uint2*)(r1 + (size_t)(row0 + rr) * 1024 + i * 256 + lane * 4); v[rr][4 * i] = bf2f(t.x & 0xffff); v[rr][4 * i + 1] = bf2f(t.x >> 16); v[rr][4 * i + 2] = bf2f(t.y & 0xffff); v[rr][4 * i + 3] = bf2f(t.y >> 16); }
;     ...
;             const float* mb = mod + (row >> 13) * 6144;
; #pragma unroll
;             for (int i = 0; i < 4; ++i) {
;                 int c = i * 256 + lane * 4;
;                 float4 sh = *(const float4*)(mb + 3072 + c), sc = *(const float4*)(mb + 4096 + c);
;                 f32x4 o;
;                 o[0] = (v[rr][4 * i] - mean) * rstd * (1.f + sc.x) + sh.x;
;                 o[1] = (v[rr][4 * i + 1] - mean) * rstd * (1.f + sc.y) + sh.y;
;                 o[2] = (v[rr][4 * i + 2] - mean) * rstd * (1.f + sc.z) + sh.z;
;                 o[3] = (v[rr][4 * i + 3] - mean) * rstd * (1.f + sc.w) + sh.w;
;                 *(uint2*)(h2 + (size_t)row * 1024 + c) = pk4(o);
	v_pk_add_f32 v[24:25], v[36:37], 1.0 op_sel_hi:[1,0]
	v_add_f32_dpp v5, v5, v5 quad_perm:[1,0,3,2] row_mask:0xf bank_mask:0xf bound_ctrl:1
	v_pk_add_f32 v[30:31], v[38:39], 1.0 op_sel_hi:[1,0]
	s_nop 0
	v_add_f32_dpp v5, v5, v5 quad_perm:[2,3,0,1] row_mask:0xf bank_mask:0xf bound_ctrl:1
	s_nop 1
	v_add_f32_dpp v5, v5, v5 row_half_mirror row_mask:0xf bank_mask:0xf bound_ctrl:1
	s_nop 1
	v_add_f32_dpp v5, v5, v5 row_mirror row_mask:0xf bank_mask:0xf bound_ctrl:1
	s_nop 0
	v_readlane_b32 s5, v5, 16
	v_readlane_b32 s4, v5, 0
	v_readlane_b32 s19, v5, 32
	v_readlane_b32 s20, v5, 48
	v_mov_b32_e32 v5, s5
	v_add_f32_e32 v5, s4, v5
	v_add_f32_e32 v5, s19, v5
	v_add_f32_e32 v5, s20, v5
	v_fmamk_f32 v5, v5, 0x3a800000, v16
	v_mul_f32_e32 v17, 0x4b800000, v5
	v_cmp_gt_f32_e64 s[4:5], s13, v5
	s_nop 1
	v_cndmask_b32_e64 v5, v5, v17, s[4:5]
	v_rsq_f32_e32 v5, v5
	s_nop 0
	v_mul_f32_e32 v17, 0x45800000, v5
	v_cndmask_b32_e64 v36, v5, v17, s[4:5]
	v_pk_mul_f32 v[38:39], v[56:57], v[36:37] op_sel_hi:[1,0]
	v_pk_mul_f32 v[32:33], v[32:33], v[36:37] op_sel_hi:[1,0]
	v_pk_fma_f32 v[24:25], v[24:25], v[38:39], v[26:27]
	v_pk_fma_f32 v[26:27], v[30:31], v[32:33], v[28:29]
	v_cvt_pk_bf16_f32 v24, v24, v25
	v_cvt_pk_bf16_f32 v25, v26, v27
	global_store_dwordx2 v[60:61], v[24:25], off
	ds_read_b128 v[24:27], v140 offset:14336
	s_nop 0
	ds_read_b128 v[28:31], v140 offset:10240
	v_pk_mul_f32 v[32:33], v[44:45], v[36:37] op_sel_hi:[1,0]
	v_pk_mul_f32 v[34:35], v[48:49], v[36:37] op_sel_hi:[1,0]
	v_cmp_lt_i32_e64 s[4:5], s18, v4
	s_or_b64 s[8:9], s[4:5], s[8:9]
	s_waitcnt vmcnt(14) lgkmcnt(1)
	v_pk_add_f32 v[24:25], v[24:25], 1.0 op_sel_hi:[1,0]
	v_pk_add_f32 v[26:27], v[26:27], 1.0 op_sel_hi:[1,0]
	s_waitcnt vmcnt(14) lgkmcnt(0)
	v_pk_fma_f32 v[24:25], v[32:33], v[24:25], v[28:29]
	v_pk_fma_f32 v[26:27], v[34:35], v[26:27], v[30:31]
	v_cvt_pk_bf16_f32 v24, v24, v25
	v_cvt_pk_bf16_f32 v25, v26, v27
	global_store_dwordx2 v[60:61], v[24:25], off offset:512
	ds_read_b128 v[24:27], v140 offset:15360
	s_nop 0
	ds_read_b128 v[28:31], v140 offset:11264
	v_pk_mul_f32 v[0:1], v[50:51], v[36:37] op_sel_hi:[1,0]
	v_pk_mul_f32 v[32:33], v[52:53], v[36:37] op_sel_hi:[1,0]
	s_waitcnt vmcnt(15) lgkmcnt(1)
	v_pk_add_f32 v[24:25], v[24:25], 1.0 op_sel_hi:[1,0]
	v_pk_add_f32 v[26:27], v[26:27], 1.0 op_sel_hi:[1,0]
	s_waitcnt vmcnt(15) lgkmcnt(0)
	v_pk_fma_f32 v[0:1], v[0:1], v[24:25], v[28:29]
	v_pk_fma_f32 v[24:25], v[32:33], v[26:27], v[30:31]
	v_cvt_pk_bf16_f32 v0, v0, v1
	v_cvt_pk_bf16_f32 v1, v24, v25
	global_store_dwordx2 v[60:61], v[0:1], off offset:1024
	ds_read_b128 v[24:27], v140 offset:16384
	ds_read_b128 v[28:31], v140 offset:12288
	v_pk_mul_f32 v[0:1], v[54:55], v[36:37] op_sel_hi:[1,0]
	v_pk_mul_f32 v[2:3], v[58:59], v[36:37] op_sel_hi:[1,0]
	s_waitcnt vmcnt(16) lgkmcnt(1)
	v_pk_add_f32 v[24:25], v[24:25], 1.0 op_sel_hi:[1,0]
	v_pk_add_f32 v[26:27], v[26:27], 1.0 op_sel_hi:[1,0]
	s_waitcnt vmcnt(16) lgkmcnt(0)
	v_pk_fma_f32 v[0:1], v[0:1], v[24:25], v[28:29]
	v_pk_fma_f32 v[2:3], v[2:3], v[26:27], v[30:31]
	v_cvt_pk_bf16_f32 v0, v0, v1
	v_cvt_pk_bf16_f32 v1, v2, v3
	global_store_dwordx2 v[60:61], v[0:1], off offset:1536
	s_andn2_b64 exec, exec, s[8:9]
	s_cbranch_execz .LBB0_998
.LBB0_990:
	v_ashrrev_i32_e32 v5, 31, v4
	v_lshlrev_b64 v[34:35], 11, v[4:5]
	v_lshl_add_u64 v[0:1], v[8:9], 0, v[34:35]
	global_load_dwordx2 v[2:3], v[0:1], off
	global_load_dwordx2 v[30:31], v[0:1], off offset:512
	global_load_dwordx2 v[32:33], v[0:1], off offset:1024
	global_load_dwordx2 v[46:47], v[0:1], off offset:1536
	v_add_u32_e32 v62, 1, v4
	v_add_u32_e32 v50, 2, v4
	v_add_u32_e32 v26, 3, v4
	v_ashrrev_i32_e32 v63, 31, v62
	v_ashrrev_i32_e32 v51, 31, v50
	v_ashrrev_i32_e32 v27, 31, v26
	v_lshlrev_b64 v[52:53], 11, v[62:63]
	v_lshlrev_b64 v[28:29], 11, v[50:51]
	v_lshlrev_b64 v[24:25], 11, v[26:27]
	v_lshl_add_u64 v[0:1], v[8:9], 0, v[52:53]
	v_lshl_add_u64 v[64:65], v[8:9], 0, v[28:29]
	v_lshl_add_u64 v[70:71], v[8:9], 0, v[24:25]
	global_load_dwordx2 v[68:69], v[0:1], off
	global_load_dwordx2 v[66:67], v[0:1], off offset:512
	global_load_dwordx2 v[42:43], v[0:1], off offset:1024
	global_load_dwordx2 v[40:41], v[0:1], off offset:1536
	global_load_dwordx2 v[60:61], v[64:65], off
	global_load_dwordx2 v[58:59], v[64:65], off offset:512
	global_load_dwordx2 v[56:57], v[64:65], off offset:1024
	global_load_dwordx2 v[54:55], v[64:65], off offset:1536
	global_load_dwordx2 v[48:49], v[70:71], off
	global_load_dwordx2 v[44:45], v[70:71], off offset:512
	global_load_dwordx2 v[38:39], v[70:71], off offset:1024
	global_load_dwordx2 v[36:37], v[70:71], off offset:1536
	s_waitcnt vmcnt(15) lgkmcnt(0)
	v_lshlrev_b32_e32 v64, 16, v2
	v_and_b32_e32 v65, 0xffff0000, v2
	v_add_f32_e32 v0, 0, v64
	v_lshlrev_b32_e32 v2, 16, v3
	v_add_f32_e32 v0, v0, v65
	v_and_b32_e32 v3, 0xffff0000, v3
	v_add_f32_e32 v0, v0, v2
	s_waitcnt vmcnt(14) lgkmcnt(0)
	v_lshlrev_b32_e32 v74, 16, v30
	v_add_f32_e32 v0, v0, v3
	v_and_b32_e32 v75, 0xffff0000, v30
	v_add_f32_e32 v0, v0, v74
	v_lshlrev_b32_e32 v30, 16, v31
	v_add_f32_e32 v0, v0, v75
	v_and_b32_e32 v31, 0xffff0000, v31
	v_add_f32_e32 v0, v0, v30
	s_waitcnt vmcnt(13) lgkmcnt(0)
	v_lshlrev_b32_e32 v78, 16, v32
	v_add_f32_e32 v0, v0, v31
	v_and_b32_e32 v79, 0xffff0000, v32
	v_add_f32_e32 v0, v0, v78
	v_lshlrev_b32_e32 v32, 16, v33
	v_add_f32_e32 v0, v0, v79
	v_and_b32_e32 v33, 0xffff0000, v33
	v_add_f32_e32 v0, v0, v32
	s_waitcnt vmcnt(12) lgkmcnt(0)
; DI void row_stats(const float (&v)[16], float& mean, float& rstd) {
;     float s = 0.f;
; #pragma unroll
;     for (int i = 0; i < 16; ++i) s += v[i];
;     mean = wsum(s) * (1.f / 1024.f);
;     float q = 0.f;
; #pragma unroll
;     for (int i = 0; i < 16; ++i) { float d = v[i] - mean; q += d * d; }
;     rstd = rsqrtf(wsum(q) * (1.f / 1024.f) + 1e-5f);
; }
; DI void phase10(const Params& p) {
;     ...
;             float mean, rstd; row_stats(v[rr], mean, rstd);
;             if (lane == 0) stats[row] = make_float2(mean, rstd);
; #pragma unroll
;             for (int i = 0; i < 4; ++i) {
;                 int c = i * 256 + lane * 4;
;                 float4 g = *(const float4*)(p.in[22] + c), bb = *(const float4*)(p.in[23] + c);
;                 v[rr][4 * i] = (v[rr][4 * i] - mean) * rstd * g.x + bb.x;
;                 v[rr][4 * i + 1] = (v[rr][4 * i + 1] - mean) * rstd * g.y + bb.y;
;                 v[rr][4 * i + 2] = (v[rr][4 * i + 2] - mean) * rstd * g.z + bb.z;
;                 v[rr][4 * i + 3] = (v[rr][4 * i + 3] - mean) * rstd * g.w + bb.w;
;             }
;             row_stats(v[rr], mean, rstd);
	v_lshlrev_b32_e32 v82, 16, v46
	v_add_f32_e32 v0, v0, v33
	v_and_b32_e32 v83, 0xffff0000, v46
	v_add_f32_e32 v0, v0, v82
	v_lshlrev_b32_e32 v46, 16, v47
	v_add_f32_e32 v0, v0, v83
	v_and_b32_e32 v47, 0xffff0000, v47
	v_add_f32_e32 v0, v0, v46
	v_add_f32_e32 v0, v0, v47
	s_nop 1
	v_add_f32_dpp v0, v0, v0 quad_perm:[1,0,3,2] row_mask:0xf bank_mask:0xf bound_ctrl:1
	s_nop 1
	v_add_f32_dpp v0, v0, v0 quad_perm:[2,3,0,1] row_mask:0xf bank_mask:0xf bound_ctrl:1
	s_nop 1
	v_add_f32_dpp v0, v0, v0 row_half_mirror row_mask:0xf bank_mask:0xf bound_ctrl:1
	s_nop 1
	v_add_f32_dpp v0, v0, v0 row_mirror row_mask:0xf bank_mask:0xf bound_ctrl:1
	s_nop 0
	v_readlane_b32 s5, v0, 16
	v_readlane_b32 s4, v0, 0
	v_readlane_b32 s19, v0, 32
	v_readlane_b32 s20, v0, 48
	v_mov_b32_e32 v0, s5
	v_add_f32_e32 v0, s4, v0
	v_add_f32_e32 v0, s19, v0
	v_add_f32_e32 v0, s20, v0
	v_mul_f32_e32 v0, 0x3a800000, v0
	v_pk_add_f32 v[70:71], v[64:65], v[0:1] op_sel_hi:[1,0] neg_lo:[0,1] neg_hi:[0,1]
	v_pk_add_f32 v[72:73], v[2:3], v[0:1] op_sel_hi:[1,0] neg_lo:[0,1] neg_hi:[0,1]
	v_pk_mul_f32 v[2:3], v[70:71], v[70:71]
	v_pk_add_f32 v[74:75], v[74:75], v[0:1] op_sel_hi:[1,0] neg_lo:[0,1] neg_hi:[0,1]
	v_pk_add_f32 v[76:77], v[30:31], v[0:1] op_sel_hi:[1,0] neg_lo:[0,1] neg_hi:[0,1]
	v_pk_add_f32 v[78:79], v[78:79], v[0:1] op_sel_hi:[1,0] neg_lo:[0,1] neg_hi:[0,1]
	v_pk_add_f32 v[80:81], v[32:33], v[0:1] op_sel_hi:[1,0] neg_lo:[0,1] neg_hi:[0,1]
	v_pk_add_f32 v[82:83], v[82:83], v[0:1] op_sel_hi:[1,0] neg_lo:[0,1] neg_hi:[0,1]
	v_pk_add_f32 v[84:85], v[46:47], v[0:1] op_sel_hi:[1,0] neg_lo:[0,1] neg_hi:[0,1]
	v_pk_mul_f32 v[30:31], v[72:73], v[72:73]
	v_add_f32_e32 v1, v2, v3
	v_add_f32_e32 v1, v30, v1
	v_pk_mul_f32 v[32:33], v[74:75], v[74:75]
	v_add_f32_e32 v1, v31, v1
	v_add_f32_e32 v1, v32, v1
	v_pk_mul_f32 v[46:47], v[76:77], v[76:77]
	v_add_f32_e32 v1, v33, v1
	v_add_f32_e32 v1, v46, v1
	v_pk_mul_f32 v[64:65], v[78:79], v[78:79]
	v_add_f32_e32 v1, v47, v1
	v_add_f32_e32 v1, v64, v1
	v_pk_mul_f32 v[86:87], v[80:81], v[80:81]
	v_add_f32_e32 v1, v65, v1
	v_add_f32_e32 v1, v86, v1
	v_pk_mul_f32 v[88:89], v[82:83], v[82:83]
	v_add_f32_e32 v1, v87, v1
	v_add_f32_e32 v1, v88, v1
	v_pk_mul_f32 v[90:91], v[84:85], v[84:85]
	v_add_f32_e32 v1, v89, v1
	v_add_f32_e32 v1, v90, v1
	v_add_f32_e32 v1, v91, v1
	s_nop 1
	v_add_f32_dpp v1, v1, v1 quad_perm:[1,0,3,2] row_mask:0xf bank_mask:0xf bound_ctrl:1
	s_nop 1
	v_add_f32_dpp v1, v1, v1 quad_perm:[2,3,0,1] row_mask:0xf bank_mask:0xf bound_ctrl:1
	s_nop 1
	v_add_f32_dpp v1, v1, v1 row_half_mirror row_mask:0xf bank_mask:0xf bound_ctrl:1
	s_nop 1
	v_add_f32_dpp v1, v1, v1 row_mirror row_mask:0xf bank_mask:0xf bound_ctrl:1
	s_nop 0
	v_readlane_b32 s5, v1, 16
	v_readlane_b32 s4, v1, 0
	v_readlane_b32 s19, v1, 32
	v_readlane_b32 s20, v1, 48
	v_mov_b32_e32 v1, s5
	v_add_f32_e32 v1, s4, v1
	v_add_f32_e32 v1, s19, v1
	v_add_f32_e32 v1, s20, v1
	v_fmamk_f32 v1, v1, 0x3a800000, v16
	v_mul_f32_e32 v2, 0x4b800000, v1
	v_cmp_gt_f32_e64 s[4:5], s13, v1
	s_nop 1
	v_cndmask_b32_e64 v1, v1, v2, s[4:5]
	v_rsq_f32_e32 v1, v1
	s_nop 0
	v_mul_f32_e32 v2, 0x45800000, v1
	v_cndmask_b32_e64 v86, v1, v2, s[4:5]
	s_and_saveexec_b64 s[4:5], vcc
	s_cbranch_execz .LBB0_992
	v_lshl_add_u64 v[2:3], v[4:5], 3, s[10:11]
	v_mov_b32_e32 v1, v86
	global_store_dwordx2 v[2:3], v[0:1], off
.LBB0_992:
	s_or_b64 exec, exec, s[4:5]
	ds_read_b128 v[88:91], v6 offset:4096
	ds_read_b128 v[92:95], v6 offset:8192
	ds_read_b128 v[96:99], v6 offset:5120
	ds_read_b128 v[100:103], v6 offset:1024
	ds_read_b128 v[104:107], v6 offset:2048
	ds_read_b128 v[108:111], v6 offset:6144
	ds_read_b128 v[112:115], v6 offset:3072
	ds_read_b128 v[116:119], v6 offset:7168
	s_waitcnt vmcnt(10) lgkmcnt(8)
	v_lshlrev_b32_e32 v126, 16, v66
	v_and_b32_e32 v127, 0xffff0000, v66
	v_lshlrev_b32_e32 v128, 16, v67
	v_and_b32_e32 v129, 0xffff0000, v67
	v_pk_mul_f32 v[66:67], v[70:71], v[86:87] op_sel_hi:[1,0]
	v_pk_mul_f32 v[70:71], v[72:73], v[86:87] op_sel_hi:[1,0]
	v_ashrrev_i32_e32 v0, 13, v4
	v_lshl_add_u32 v140, v0, 13, v6
	v_mul_i32_i24_e32 v0, 0x1800, v0
	v_pk_mul_f32 v[72:73], v[74:75], v[86:87] op_sel_hi:[1,0]
	v_ashrrev_i32_e32 v1, 31, v0
	v_lshl_add_u64 v[0:1], v[0:1], 2, s[50:51]
	v_pk_mul_f32 v[74:75], v[76:77], v[86:87] op_sel_hi:[1,0]
	v_lshl_add_u64 v[64:65], v[0:1], 0, s[16:17]
	v_lshl_add_u64 v[30:31], v[64:65], 0, v[6:7]
	v_lshl_add_u64 v[46:47], v[0:1], 0, s[14:15]
	v_pk_mul_f32 v[76:77], v[78:79], v[86:87] op_sel_hi:[1,0]
	ds_read_b128 v[120:123], v140 offset:13312
	v_lshl_add_u64 v[32:33], v[46:47], 0, v[6:7]
	ds_read_b128 v[0:3], v140 offset:9216
	v_pk_mul_f32 v[78:79], v[80:81], v[86:87] op_sel_hi:[1,0]
	v_pk_mul_f32 v[80:81], v[82:83], v[86:87] op_sel_hi:[1,0]
	v_pk_mul_f32 v[82:83], v[84:85], v[86:87] op_sel_hi:[1,0]
	v_lshlrev_b32_e32 v124, 16, v68
	v_and_b32_e32 v125, 0xffff0000, v68
	v_add_f32_e32 v5, 0, v124
	v_lshlrev_b32_e32 v68, 16, v69
	v_add_f32_e32 v5, v5, v125
	v_and_b32_e32 v69, 0xffff0000, v69
	v_add_f32_e32 v5, v5, v68
	v_add_f32_e32 v5, v5, v69
	v_add_f32_e32 v5, v5, v126
	v_add_f32_e32 v5, v5, v127
	v_add_f32_e32 v5, v5, v128
	s_waitcnt vmcnt(9) lgkmcnt(10)
	v_lshlrev_b32_e32 v130, 16, v42
	v_add_f32_e32 v5, v5, v129
	v_and_b32_e32 v131, 0xffff0000, v42
	v_add_f32_e32 v5, v5, v130
	v_lshlrev_b32_e32 v42, 16, v43
	v_add_f32_e32 v5, v5, v131
	v_and_b32_e32 v43, 0xffff0000, v43
	v_add_f32_e32 v5, v5, v42
	s_waitcnt vmcnt(8) lgkmcnt(10)
	v_lshlrev_b32_e32 v132, 16, v40
	v_add_f32_e32 v5, v5, v43
	v_and_b32_e32 v133, 0xffff0000, v40
	v_add_f32_e32 v5, v5, v132
	v_lshlrev_b32_e32 v40, 16, v41
	v_add_f32_e32 v5, v5, v133
	v_and_b32_e32 v41, 0xffff0000, v41
	v_add_f32_e32 v5, v5, v40
	v_add_f32_e32 v5, v5, v41
	v_mov_b32_e32 v19, v7
	v_mov_b32_e32 v21, v7
	v_add_f32_dpp v5, v5, v5 quad_perm:[1,0,3,2] row_mask:0xf bank_mask:0xf bound_ctrl:1
	v_mov_b32_e32 v23, v7
	s_waitcnt vmcnt(0) lgkmcnt(8)
; DI void row_stats(const float (&v)[16], float& mean, float& rstd) {
;     float s = 0.f;
; #pragma unroll
;     for (int i = 0; i < 16; ++i) s += v[i];
;     mean = wsum(s) * (1.f / 1024.f);
;     float q = 0.f;
; #pragma unroll
;     for (int i = 0; i < 16; ++i) { float d = v[i] - mean; q += d * d; }
;     rstd = rsqrtf(wsum(q) * (1.f / 1024.f) + 1e-5f);
; }
; DI void phase10(const Params& p) {
;     ...
;             for (int i = 0; i < 4; ++i) {
;                 int c = i * 256 + lane * 4;
;                 float4 g = *(const float4*)(p.in[22] + c), bb = *(const float4*)(p.in[23] + c);
;                 v[rr][4 * i] = (v[rr][4 * i] - mean) * rstd * g.x + bb.x;
;                 v[rr][4 * i + 1] = (v[rr][4 * i + 1] - mean) * rstd * g.y + bb.y;
;                 v[rr][4 * i + 2] = (v[rr][4 * i + 2] - mean) * rstd * g.z + bb.z;
;                 v[rr][4 * i + 3] = (v[rr][4 * i + 3] - mean) * rstd * g.w + bb.w;
;             }
;             row_stats(v[rr], mean, rstd);
	v_pk_fma_f32 v[80:81], v[80:81], v[88:89], v[92:93]
	v_pk_fma_f32 v[82:83], v[82:83], v[90:91], v[94:95]
	s_waitcnt vmcnt(0) lgkmcnt(6)
	v_pk_fma_f32 v[66:67], v[66:67], v[100:101], v[96:97]
	v_pk_fma_f32 v[70:71], v[70:71], v[102:103], v[98:99]
	v_add_f32_e32 v17, 0, v66
	v_add_f32_e32 v17, v17, v67
	v_add_f32_e32 v17, v17, v70
	s_waitcnt vmcnt(0) lgkmcnt(4)
	v_pk_fma_f32 v[72:73], v[72:73], v[104:105], v[108:109]
	v_add_f32_e32 v17, v17, v71
	v_add_f32_e32 v17, v17, v72
	v_pk_fma_f32 v[74:75], v[74:75], v[106:107], v[110:111]
	v_add_f32_e32 v17, v17, v73
	v_add_f32_e32 v17, v17, v74
	s_waitcnt vmcnt(0) lgkmcnt(2)
	v_pk_fma_f32 v[76:77], v[76:77], v[112:113], v[116:117]
	v_add_f32_e32 v17, v17, v75
	v_add_f32_e32 v17, v17, v76
	v_pk_fma_f32 v[78:79], v[78:79], v[114:115], v[118:119]
	v_add_f32_e32 v17, v17, v77
	v_add_f32_e32 v17, v17, v78
	v_add_f32_e32 v17, v17, v79
	v_add_f32_e32 v17, v17, v80
	v_add_f32_e32 v17, v17, v81
	v_add_f32_e32 v17, v17, v82
	v_add_f32_e32 v17, v17, v83
	v_add_f32_dpp v5, v5, v5 quad_perm:[2,3,0,1] row_mask:0xf bank_mask:0xf bound_ctrl:1
	s_waitcnt vmcnt(0) lgkmcnt(1)
	v_pk_add_f32 v[84:85], v[120:121], 1.0 op_sel_hi:[1,0]
	v_add_f32_dpp v17, v17, v17 quad_perm:[1,0,3,2] row_mask:0xf bank_mask:0xf bound_ctrl:1
	v_add_f32_dpp v5, v5, v5 row_half_mirror row_mask:0xf bank_mask:0xf bound_ctrl:1
	v_pk_add_f32 v[86:87], v[122:123], 1.0 op_sel_hi:[1,0]
	v_add_f32_dpp v17, v17, v17 quad_perm:[2,3,0,1] row_mask:0xf bank_mask:0xf bound_ctrl:1
	v_add_f32_dpp v5, v5, v5 row_mirror row_mask:0xf bank_mask:0xf bound_ctrl:1
	s_nop 0
	v_add_f32_dpp v17, v17, v17 row_half_mirror row_mask:0xf bank_mask:0xf bound_ctrl:1
	s_nop 1
	v_add_f32_dpp v17, v17, v17 row_mirror row_mask:0xf bank_mask:0xf bound_ctrl:1
	s_nop 0
	v_readlane_b32 s5, v17, 16
	v_readlane_b32 s4, v17, 0
	v_readlane_b32 s19, v17, 32
	v_readlane_b32 s20, v17, 48
	v_mov_b32_e32 v17, s5
	v_add_f32_e32 v17, s4, v17
	v_add_f32_e32 v17, s19, v17
	v_add_f32_e32 v17, s20, v17
	v_mul_f32_e32 v88, 0x3a800000, v17
	v_pk_add_f32 v[90:91], v[66:67], v[88:89] op_sel_hi:[1,0] neg_lo:[0,1] neg_hi:[0,1]
	v_pk_add_f32 v[92:93], v[70:71], v[88:89] op_sel_hi:[1,0] neg_lo:[0,1] neg_hi:[0,1]
	v_pk_mul_f32 v[66:67], v[90:91], v[90:91]
	v_pk_mul_f32 v[70:71], v[92:93], v[92:93]
	v_add_f32_e32 v17, v66, v67
	v_pk_add_f32 v[94:95], v[72:73], v[88:89] op_sel_hi:[1,0] neg_lo:[0,1] neg_hi:[0,1]
	v_add_f32_e32 v17, v70, v17
	v_pk_mul_f32 v[72:73], v[94:95], v[94:95]
	v_add_f32_e32 v17, v71, v17
	v_pk_add_f32 v[96:97], v[74:75], v[88:89] op_sel_hi:[1,0] neg_lo:[0,1] neg_hi:[0,1]
	v_add_f32_e32 v17, v72, v17
	v_pk_mul_f32 v[74:75], v[96:97], v[96:97]
	v_add_f32_e32 v17, v73, v17
	v_pk_add_f32 v[98:99], v[76:77], v[88:89] op_sel_hi:[1,0] neg_lo:[0,1] neg_hi:[0,1]
	v_add_f32_e32 v17, v74, v17
	v_pk_mul_f32 v[76:77], v[98:99], v[98:99]
	v_add_f32_e32 v17, v75, v17
	v_pk_add_f32 v[100:101], v[78:79], v[88:89] op_sel_hi:[1,0] neg_lo:[0,1] neg_hi:[0,1]
	v_add_f32_e32 v17, v76, v17
	v_pk_mul_f32 v[78:79], v[100:101], v[100:101]
	v_add_f32_e32 v17, v77, v17
	v_pk_add_f32 v[102:103], v[80:81], v[88:89] op_sel_hi:[1,0] neg_lo:[0,1] neg_hi:[0,1]
	v_add_f32_e32 v17, v78, v17
	v_pk_mul_f32 v[80:81], v[102:103], v[102:103]
	v_add_f32_e32 v17, v79, v17
	v_pk_add_f32 v[104:105], v[82:83], v[88:89] op_sel_hi:[1,0] neg_lo:[0,1] neg_hi:[0,1]
	v_add_f32_e32 v17, v80, v17
	v_pk_mul_f32 v[82:83], v[104:105], v[104:105]
	v_add_f32_e32 v17, v81, v17
	v_add_f32_e32 v17, v82, v17
	v_add_f32_e32 v17, v83, v17
	v_readlane_b32 s20, v5, 16
	v_readlane_b32 s4, v5, 0
	v_add_f32_dpp v17, v17, v17 quad_perm:[1,0,3,2] row_mask:0xf bank_mask:0xf bound_ctrl:1
	s_nop 1
	v_add_f32_dpp v17, v17, v17 quad_perm:[2,3,0,1] row_mask:0xf bank_mask:0xf bound_ctrl:1
	s_nop 1
	v_add_f32_dpp v17, v17, v17 row_half_mirror row_mask:0xf bank_mask:0xf bound_ctrl:1
	s_nop 1
	v_add_f32_dpp v17, v17, v17 row_mirror row_mask:0xf bank_mask:0xf bound_ctrl:1
	s_nop 0
	v_readlane_b32 s5, v17, 0
	v_readlane_b32 s19, v17, 16
	v_readlane_b32 s21, v17, 32
	v_readlane_b32 s23, v17, 48
	v_mov_b32_e32 v17, s20
	v_add_f32_e32 v17, s4, v17
	v_readlane_b32 s4, v5, 32
	s_nop 1
	v_add_f32_e32 v17, s4, v17
	v_readlane_b32 s4, v5, 48
	s_nop 1
	v_add_f32_e32 v5, s4, v17
	v_mul_f32_e32 v82, 0x3a800000, v5
	v_pk_add_f32 v[66:67], v[124:125], v[82:83] op_sel_hi:[1,0] neg_lo:[0,1] neg_hi:[0,1]
	v_pk_add_f32 v[68:69], v[68:69], v[82:83] op_sel_hi:[1,0] neg_lo:[0,1] neg_hi:[0,1]
	v_pk_mul_f32 v[88:89], v[66:67], v[66:67]
	v_pk_mul_f32 v[106:107], v[68:69], v[68:69]
	v_add_f32_e32 v5, v88, v89
	v_pk_add_f32 v[70:71], v[126:127], v[82:83] op_sel_hi:[1,0] neg_lo:[0,1] neg_hi:[0,1]
	v_add_f32_e32 v5, v106, v5
	v_pk_mul_f32 v[108:109], v[70:71], v[70:71]
	v_add_f32_e32 v5, v107, v5
	v_pk_add_f32 v[72:73], v[128:129], v[82:83] op_sel_hi:[1,0] neg_lo:[0,1] neg_hi:[0,1]
	v_add_f32_e32 v5, v108, v5
	v_pk_mul_f32 v[110:111], v[72:73], v[72:73]
	v_add_f32_e32 v5, v109, v5
	v_pk_add_f32 v[74:75], v[130:131], v[82:83] op_sel_hi:[1,0] neg_lo:[0,1] neg_hi:[0,1]
	v_add_f32_e32 v5, v110, v5
	v_pk_mul_f32 v[112:113], v[74:75], v[74:75]
	v_add_f32_e32 v5, v111, v5
	v_pk_add_f32 v[76:77], v[42:43], v[82:83] op_sel_hi:[1,0] neg_lo:[0,1] neg_hi:[0,1]
	v_add_f32_e32 v5, v112, v5
	v_pk_mul_f32 v[42:43], v[76:77], v[76:77]
	v_add_f32_e32 v5, v113, v5
	v_pk_add_f32 v[78:79], v[132:133], v[82:83] op_sel_hi:[1,0] neg_lo:[0,1] neg_hi:[0,1]
	v_add_f32_e32 v5, v42, v5
	v_pk_mul_f32 v[114:115], v[78:79], v[78:79]
	v_add_f32_e32 v5, v43, v5
	v_pk_add_f32 v[80:81], v[40:41], v[82:83] op_sel_hi:[1,0] neg_lo:[0,1] neg_hi:[0,1]
	v_add_f32_e32 v5, v114, v5
	v_pk_mul_f32 v[40:41], v[80:81], v[80:81]
	v_add_f32_e32 v5, v115, v5
	v_add_f32_e32 v5, v40, v5
	v_add_f32_e32 v5, v41, v5
	v_mov_b32_e32 v41, s19
	v_lshl_add_u64 v[108:109], v[14:15], 0, v[34:35]
	v_add_f32_dpp v5, v5, v5 quad_perm:[1,0,3,2] row_mask:0xf bank_mask:0xf bound_ctrl:1
	v_lshl_add_u64 v[34:35], v[64:65], 0, v[18:19]
	s_nop 0
	v_add_f32_dpp v5, v5, v5 quad_perm:[2,3,0,1] row_mask:0xf bank_mask:0xf bound_ctrl:1
	s_nop 1
	v_add_f32_dpp v5, v5, v5 row_half_mirror row_mask:0xf bank_mask:0xf bound_ctrl:1
	s_nop 1
	v_add_f32_dpp v5, v5, v5 row_mirror row_mask:0xf bank_mask:0xf bound_ctrl:1
	s_nop 0
	v_readlane_b32 s24, v5, 16
	v_readlane_b32 s4, v5, 0
	v_readlane_b32 s20, v5, 32
	v_mov_b32_e32 v40, s24
	v_pk_add_f32 v[40:41], s[4:5], v[40:41]
	v_readlane_b32 s22, v5, 48
	v_pk_add_f32 v[40:41], v[40:41], s[20:21]
	s_nop 0
	v_pk_add_f32 v[40:41], v[40:41], s[22:23]
	s_nop 0
	v_pk_fma_f32 v[106:107], v[40:41], s[12:13], v[16:17] op_sel_hi:[1,0,0]
	s_nop 0
	v_mul_f32_e32 v5, 0x4b800000, v107
	v_cmp_gt_f32_e64 s[4:5], s13, v107
	s_nop 1
	v_cndmask_b32_e64 v5, v107, v5, s[4:5]
	v_rsq_f32_e32 v5, v5
	s_nop 0
	v_mul_f32_e32 v17, 0x45800000, v5
	v_cndmask_b32_e64 v110, v5, v17, s[4:5]
	v_pk_mul_f32 v[40:41], v[90:91], v[110:111] op_sel_hi:[1,0]
	v_pk_mul_f32 v[42:43], v[96:97], v[110:111] op_sel_hi:[1,0]
	s_waitcnt vmcnt(0) lgkmcnt(0)
; DI uint2 pk4(f32x4 v) { return make_uint2(pk2(v[0], v[1]), pk2(v[2], v[3])); }
; DI void phase10(const Params& p) {
;     ...
;             if (lane == 0) stats[row] = make_float2(mean, rstd);
; #pragma unroll
;             for (int i = 0; i < 4; ++i) {
;                 int c = i * 256 + lane * 4;
;                 float4 g = *(const float4*)(p.in[22] + c), bb = *(const float4*)(p.in[23] + c);
;                 v[rr][4 * i] = (v[rr][4 * i] - mean) * rstd * g.x + bb.x;
;                 v[rr][4 * i + 1] = (v[rr][4 * i + 1] - mean) * rstd * g.y + bb.y;
;                 v[rr][4 * i + 2] = (v[rr][4 * i + 2] - mean) * rstd * g.z + bb.z;
;                 v[rr][4 * i + 3] = (v[rr][4 * i + 3] - mean) * rstd * g.w + bb.w;
;             }
;             row_stats(v[rr], mean, rstd);
;             const float* mb = mod + (row >> 13) * 6144;
; #pragma unroll
;             for (int i = 0; i < 4; ++i) {
;                 int c = i * 256 + lane * 4;
;                 float4 sh = *(const float4*)(mb + 3072 + c), sc = *(const float4*)(mb + 4096 + c);
;                 f32x4 o;
;                 o[0] = (v[rr][4 * i] - mean) * rstd * (1.f + sc.x) + sh.x;
;                 o[1] = (v[rr][4 * i + 1] - mean) * rstd * (1.f + sc.y) + sh.y;
;                 o[2] = (v[rr][4 * i + 2] - mean) * rstd * (1.f + sc.z) + sh.z;
;                 o[3] = (v[rr][4 * i + 3] - mean) * rstd * (1.f + sc.w) + sh.w;
;                 *(uint2*)(h2 + (size_t)row * 1024 + c) = pk4(o);
	v_pk_fma_f32 v[0:1], v[84:85], v[40:41], v[0:1]
	v_pk_mul_f32 v[40:41], v[92:93], v[110:111] op_sel_hi:[1,0]
	v_cvt_pk_bf16_f32 v0, v0, v1
	v_pk_fma_f32 v[2:3], v[86:87], v[40:41], v[2:3]
	v_lshl_add_u64 v[40:41], v[46:47], 0, v[18:19]
	v_cvt_pk_bf16_f32 v1, v2, v3
	global_store_dwordx2 v[108:109], v[0:1], off
	ds_read_b128 v[84:87], v140 offset:14336
	ds_read_b128 v[88:91], v140 offset:10240
	v_pk_mul_f32 v[2:3], v[94:95], v[110:111] op_sel_hi:[1,0]
	v_lshl_add_u64 v[0:1], v[64:65], 0, v[20:21]
	v_pk_mul_f32 v[92:93], v[100:101], v[110:111] op_sel_hi:[1,0]
	v_mul_f32_e32 v5, 0x4b800000, v106
	v_cmp_gt_f32_e64 s[4:5], s13, v106
	s_waitcnt vmcnt(1) lgkmcnt(1)
	v_pk_add_f32 v[84:85], v[84:85], 1.0 op_sel_hi:[1,0]
	v_pk_add_f32 v[86:87], v[86:87], 1.0 op_sel_hi:[1,0]
	s_waitcnt vmcnt(1) lgkmcnt(0)
	v_pk_fma_f32 v[2:3], v[2:3], v[84:85], v[88:89]
	v_pk_fma_f32 v[42:43], v[42:43], v[86:87], v[90:91]
	v_cvt_pk_bf16_f32 v2, v2, v3
	v_cvt_pk_bf16_f32 v3, v42, v43
	global_store_dwordx2 v[108:109], v[2:3], off offset:512
	ds_read_b128 v[84:87], v140 offset:15360
	v_lshl_add_u64 v[42:43], v[46:47], 0, v[20:21]
	ds_read_b128 v[88:91], v140 offset:11264
	v_lshl_add_u64 v[2:3], v[64:65], 0, v[22:23]
	v_pk_mul_f32 v[64:65], v[98:99], v[110:111] op_sel_hi:[1,0]
	v_lshl_add_u64 v[46:47], v[46:47], 0, v[22:23]
	v_cndmask_b32_e64 v5, v106, v5, s[4:5]
	v_rsq_f32_e32 v5, v5
	s_waitcnt vmcnt(2) lgkmcnt(1)
	v_pk_add_f32 v[84:85], v[84:85], 1.0 op_sel_hi:[1,0]
	v_pk_add_f32 v[86:87], v[86:87], 1.0 op_sel_hi:[1,0]
	s_waitcnt vmcnt(2) lgkmcnt(0)
	v_pk_fma_f32 v[64:65], v[64:65], v[84:85], v[88:89]
	v_pk_fma_f32 v[84:85], v[92:93], v[86:87], v[90:91]
	v_cvt_pk_bf16_f32 v64, v64, v65
	v_cvt_pk_bf16_f32 v65, v84, v85
	global_store_dwordx2 v[108:109], v[64:65], off offset:1024
	ds_read_b128 v[84:87], v140 offset:16384
	ds_read_b128 v[88:91], v140 offset:12288
	v_pk_mul_f32 v[64:65], v[102:103], v[110:111] op_sel_hi:[1,0]
	v_pk_mul_f32 v[92:93], v[104:105], v[110:111] op_sel_hi:[1,0]
	v_mul_f32_e32 v17, 0x45800000, v5
	s_waitcnt vmcnt(3) lgkmcnt(1)
	v_pk_add_f32 v[84:85], v[84:85], 1.0 op_sel_hi:[1,0]
	v_pk_add_f32 v[86:87], v[86:87], 1.0 op_sel_hi:[1,0]
	s_waitcnt vmcnt(3) lgkmcnt(0)
	v_pk_fma_f32 v[64:65], v[64:65], v[84:85], v[88:89]
	v_pk_fma_f32 v[84:85], v[92:93], v[86:87], v[90:91]
	v_cvt_pk_bf16_f32 v64, v64, v65
	v_cvt_pk_bf16_f32 v65, v84, v85
	global_store_dwordx2 v[108:109], v[64:65], off offset:1536
	v_cndmask_b32_e64 v64, v5, v17, s[4:5]
	s_and_saveexec_b64 s[4:5], vcc
	s_cbranch_execz .LBB0_994
	v_lshl_add_u64 v[62:63], v[62:63], 3, s[10:11]
	v_mov_b32_e32 v83, v64
	global_store_dwordx2 v[62:63], v[82:83], off
.LBB0_994:
	s_or_b64 exec, exec, s[4:5]
	ds_read_b128 v[82:85], v6 offset:4096
	ds_read_b128 v[86:89], v6 offset:8192
	ds_read_b128 v[90:93], v6 offset:5120
	ds_read_b128 v[94:97], v6 offset:1024
	ds_read_b128 v[98:101], v6 offset:2048
	ds_read_b128 v[102:105], v6 offset:6144
	ds_read_b128 v[106:109], v6 offset:3072
	ds_read_b128 v[110:113], v6 offset:7168
	v_lshlrev_b32_e32 v122, 16, v54
	v_and_b32_e32 v123, 0xffff0000, v54
	v_lshlrev_b32_e32 v124, 16, v55
	v_and_b32_e32 v125, 0xffff0000, v55
	v_pk_mul_f32 v[54:55], v[66:67], v[64:65] op_sel_hi:[1,0]
	v_lshlrev_b32_e32 v118, 16, v56
	v_and_b32_e32 v119, 0xffff0000, v56
	v_lshlrev_b32_e32 v120, 16, v57
	v_and_b32_e32 v121, 0xffff0000, v57
	v_pk_mul_f32 v[56:57], v[68:69], v[64:65] op_sel_hi:[1,0]
	v_lshlrev_b32_e32 v114, 16, v58
	v_and_b32_e32 v115, 0xffff0000, v58
	v_lshlrev_b32_e32 v116, 16, v59
	v_and_b32_e32 v117, 0xffff0000, v59
	v_pk_mul_f32 v[58:59], v[70:71], v[64:65] op_sel_hi:[1,0]
	v_pk_mul_f32 v[66:67], v[72:73], v[64:65] op_sel_hi:[1,0]
	v_pk_mul_f32 v[68:69], v[74:75], v[64:65] op_sel_hi:[1,0]
	v_pk_mul_f32 v[70:71], v[76:77], v[64:65] op_sel_hi:[1,0]
	v_pk_mul_f32 v[126:127], v[78:79], v[64:65] op_sel_hi:[1,0]
	ds_read_b128 v[72:75], v140 offset:9216
	ds_read_b128 v[76:79], v140 offset:13312
	v_pk_mul_f32 v[64:65], v[80:81], v[64:65] op_sel_hi:[1,0]
	v_lshlrev_b32_e32 v62, 16, v60
	v_and_b32_e32 v63, 0xffff0000, v60
	v_add_f32_e32 v5, 0, v62
	v_lshlrev_b32_e32 v60, 16, v61
	v_add_f32_e32 v5, v5, v63
	v_and_b32_e32 v61, 0xffff0000, v61
	v_add_f32_e32 v5, v5, v60
	v_add_f32_e32 v5, v5, v61
	v_add_f32_e32 v5, v5, v114
	v_add_f32_e32 v5, v5, v115
	v_add_f32_e32 v5, v5, v116
	v_add_f32_e32 v5, v5, v117
	v_add_f32_e32 v5, v5, v118
	v_add_f32_e32 v5, v5, v119
	v_add_f32_e32 v5, v5, v120
	v_add_f32_e32 v5, v5, v121
	v_add_f32_e32 v5, v5, v122
	v_add_f32_e32 v5, v5, v123
	v_add_f32_e32 v5, v5, v124
	v_add_f32_e32 v5, v5, v125
	v_lshl_add_u64 v[52:53], v[14:15], 0, v[52:53]
	s_waitcnt vmcnt(4) lgkmcnt(8)
	v_pk_fma_f32 v[80:81], v[126:127], v[82:83], v[86:87]
	v_pk_fma_f32 v[64:65], v[64:65], v[84:85], v[88:89]
	s_waitcnt vmcnt(4) lgkmcnt(6)
	v_pk_fma_f32 v[54:55], v[54:55], v[94:95], v[90:91]
	v_pk_fma_f32 v[56:57], v[56:57], v[96:97], v[92:93]
	v_add_f32_e32 v17, 0, v54
	v_add_f32_e32 v17, v17, v55
	v_add_f32_e32 v17, v17, v56
	s_waitcnt vmcnt(4) lgkmcnt(4)
	v_pk_fma_f32 v[58:59], v[58:59], v[98:99], v[102:103]
	v_add_f32_e32 v17, v17, v57
	v_add_f32_e32 v17, v17, v58
	v_pk_fma_f32 v[66:67], v[66:67], v[100:101], v[104:105]
	v_add_f32_e32 v17, v17, v59
	v_add_f32_e32 v17, v17, v66
	s_waitcnt vmcnt(4) lgkmcnt(2)
	v_pk_fma_f32 v[68:69], v[68:69], v[106:107], v[110:111]
	v_add_f32_e32 v17, v17, v67
	v_add_f32_e32 v17, v17, v68
	v_pk_fma_f32 v[70:71], v[70:71], v[108:109], v[112:113]
	v_add_f32_e32 v17, v17, v69
	v_add_f32_e32 v17, v17, v70
	v_add_f32_e32 v17, v17, v71
	v_add_f32_e32 v17, v17, v80
	v_add_f32_e32 v17, v17, v81
	v_add_f32_e32 v17, v17, v64
	v_add_f32_e32 v17, v17, v65
	v_add_f32_dpp v5, v5, v5 quad_perm:[1,0,3,2] row_mask:0xf bank_mask:0xf bound_ctrl:1
	s_waitcnt vmcnt(4) lgkmcnt(0)
; DI uint2 pk4(f32x4 v) { return make_uint2(pk2(v[0], v[1]), pk2(v[2], v[3])); }
; DI void row_stats(const float (&v)[16], float& mean, float& rstd) {
;     float s = 0.f;
; #pragma unroll
;     for (int i = 0; i < 16; ++i) s += v[i];
;     mean = wsum(s) * (1.f / 1024.f);
;     float q = 0.f;
; #pragma unroll
;     for (int i = 0; i < 16; ++i) { float d = v[i] - mean; q += d * d; }
;     rstd = rsqrtf(wsum(q) * (1.f / 1024.f) + 1e-5f);
; }
; DI void phase10(const Params& p) {
;     ...
;             row_stats(v[rr], mean, rstd);
;             const float* mb = mod + (row >> 13) * 6144;
; #pragma unroll
;             for (int i = 0; i < 4; ++i) {
;                 int c = i * 256 + lane * 4;
;                 float4 sh = *(const float4*)(mb + 3072 + c), sc = *(const float4*)(mb + 4096 + c);
;                 f32x4 o;
;                 o[0] = (v[rr][4 * i] - mean) * rstd * (1.f + sc.x) + sh.x;
;                 o[1] = (v[rr][4 * i + 1] - mean) * rstd * (1.f + sc.y) + sh.y;
;                 o[2] = (v[rr][4 * i + 2] - mean) * rstd * (1.f + sc.z) + sh.z;
;                 o[3] = (v[rr][4 * i + 3] - mean) * rstd * (1.f + sc.w) + sh.w;
;                 *(uint2*)(h2 + (size_t)row * 1024 + c) = pk4(o);
	v_pk_add_f32 v[76:77], v[76:77], 1.0 op_sel_hi:[1,0]
	v_add_f32_dpp v17, v17, v17 quad_perm:[1,0,3,2] row_mask:0xf bank_mask:0xf bound_ctrl:1
	v_add_f32_dpp v5, v5, v5 quad_perm:[2,3,0,1] row_mask:0xf bank_mask:0xf bound_ctrl:1
	v_pk_add_f32 v[78:79], v[78:79], 1.0 op_sel_hi:[1,0]
	v_add_f32_dpp v17, v17, v17 quad_perm:[2,3,0,1] row_mask:0xf bank_mask:0xf bound_ctrl:1
	v_add_f32_dpp v5, v5, v5 row_half_mirror row_mask:0xf bank_mask:0xf bound_ctrl:1
	s_nop 0
	v_add_f32_dpp v17, v17, v17 row_half_mirror row_mask:0xf bank_mask:0xf bound_ctrl:1
	v_add_f32_dpp v5, v5, v5 row_mirror row_mask:0xf bank_mask:0xf bound_ctrl:1
	s_nop 0
	v_add_f32_dpp v17, v17, v17 row_mirror row_mask:0xf bank_mask:0xf bound_ctrl:1
	s_nop 0
	v_readlane_b32 s5, v17, 16
	v_readlane_b32 s4, v17, 0
	v_readlane_b32 s19, v17, 32
	v_readlane_b32 s20, v17, 48
	v_mov_b32_e32 v17, s5
	v_add_f32_e32 v17, s4, v17
	v_add_f32_e32 v17, s19, v17
	v_add_f32_e32 v17, s20, v17
	v_mul_f32_e32 v82, 0x3a800000, v17
	v_pk_add_f32 v[84:85], v[54:55], v[82:83] op_sel_hi:[1,0] neg_lo:[0,1] neg_hi:[0,1]
	v_pk_add_f32 v[86:87], v[56:57], v[82:83] op_sel_hi:[1,0] neg_lo:[0,1] neg_hi:[0,1]
	v_pk_mul_f32 v[54:55], v[84:85], v[84:85]
	v_pk_mul_f32 v[56:57], v[86:87], v[86:87]
	v_add_f32_e32 v17, v54, v55
	v_pk_add_f32 v[88:89], v[58:59], v[82:83] op_sel_hi:[1,0] neg_lo:[0,1] neg_hi:[0,1]
	v_add_f32_e32 v17, v56, v17
	v_pk_mul_f32 v[58:59], v[88:89], v[88:89]
	v_add_f32_e32 v17, v57, v17
	v_pk_add_f32 v[90:91], v[66:67], v[82:83] op_sel_hi:[1,0] neg_lo:[0,1] neg_hi:[0,1]
	v_add_f32_e32 v17, v58, v17
	v_pk_add_f32 v[92:93], v[68:69], v[82:83] op_sel_hi:[1,0] neg_lo:[0,1] neg_hi:[0,1]
	v_pk_add_f32 v[94:95], v[70:71], v[82:83] op_sel_hi:[1,0] neg_lo:[0,1] neg_hi:[0,1]
	v_pk_add_f32 v[80:81], v[80:81], v[82:83] op_sel_hi:[1,0] neg_lo:[0,1] neg_hi:[0,1]
	v_pk_add_f32 v[82:83], v[64:65], v[82:83] op_sel_hi:[1,0] neg_lo:[0,1] neg_hi:[0,1]
	v_pk_mul_f32 v[64:65], v[90:91], v[90:91]
	v_add_f32_e32 v17, v59, v17
	v_add_f32_e32 v17, v64, v17
	v_pk_mul_f32 v[66:67], v[92:93], v[92:93]
	v_add_f32_e32 v17, v65, v17
	v_add_f32_e32 v17, v66, v17
	v_pk_mul_f32 v[68:69], v[94:95], v[94:95]
	v_add_f32_e32 v17, v67, v17
	v_add_f32_e32 v17, v68, v17
	v_pk_mul_f32 v[70:71], v[80:81], v[80:81]
	v_add_f32_e32 v17, v69, v17
	v_add_f32_e32 v17, v70, v17
	v_pk_mul_f32 v[96:97], v[82:83], v[82:83]
	v_add_f32_e32 v17, v71, v17
	v_add_f32_e32 v17, v96, v17
	v_add_f32_e32 v17, v97, v17
	v_readlane_b32 s20, v5, 16
	v_readlane_b32 s4, v5, 0
	v_add_f32_dpp v17, v17, v17 quad_perm:[1,0,3,2] row_mask:0xf bank_mask:0xf bound_ctrl:1
	s_nop 1
	v_add_f32_dpp v17, v17, v17 quad_perm:[2,3,0,1] row_mask:0xf bank_mask:0xf bound_ctrl:1
	s_nop 1
	v_add_f32_dpp v17, v17, v17 row_half_mirror row_mask:0xf bank_mask:0xf bound_ctrl:1
	s_nop 1
	v_add_f32_dpp v17, v17, v17 row_mirror row_mask:0xf bank_mask:0xf bound_ctrl:1
	s_nop 0
	v_readlane_b32 s5, v17, 0
	v_readlane_b32 s19, v17, 16
	v_readlane_b32 s21, v17, 32
	v_readlane_b32 s23, v17, 48
	v_mov_b32_e32 v17, s20
	v_add_f32_e32 v17, s4, v17
	v_readlane_b32 s4, v5, 32
	s_nop 1
	v_add_f32_e32 v17, s4, v17
	v_readlane_b32 s4, v5, 48
	s_nop 1
	v_add_f32_e32 v5, s4, v17
	v_mul_f32_e32 v70, 0x3a800000, v5
	v_pk_add_f32 v[54:55], v[62:63], v[70:71] op_sel_hi:[1,0] neg_lo:[0,1] neg_hi:[0,1]
	v_pk_add_f32 v[56:57], v[60:61], v[70:71] op_sel_hi:[1,0] neg_lo:[0,1] neg_hi:[0,1]
	v_pk_mul_f32 v[96:97], v[54:55], v[54:55]
	v_pk_mul_f32 v[98:99], v[56:57], v[56:57]
	v_add_f32_e32 v5, v96, v97
	v_pk_add_f32 v[58:59], v[114:115], v[70:71] op_sel_hi:[1,0] neg_lo:[0,1] neg_hi:[0,1]
	v_add_f32_e32 v5, v98, v5
	v_pk_mul_f32 v[100:101], v[58:59], v[58:59]
	v_add_f32_e32 v5, v99, v5
	v_pk_add_f32 v[60:61], v[116:117], v[70:71] op_sel_hi:[1,0] neg_lo:[0,1] neg_hi:[0,1]
	v_add_f32_e32 v5, v100, v5
	v_pk_mul_f32 v[102:103], v[60:61], v[60:61]
	v_add_f32_e32 v5, v101, v5
	v_pk_add_f32 v[62:63], v[118:119], v[70:71] op_sel_hi:[1,0] neg_lo:[0,1] neg_hi:[0,1]
	v_add_f32_e32 v5, v102, v5
	v_pk_mul_f32 v[104:105], v[62:63], v[62:63]
	v_add_f32_e32 v5, v103, v5
	v_pk_add_f32 v[64:65], v[120:121], v[70:71] op_sel_hi:[1,0] neg_lo:[0,1] neg_hi:[0,1]
	v_add_f32_e32 v5, v104, v5
	v_pk_mul_f32 v[106:107], v[64:65], v[64:65]
	v_add_f32_e32 v5, v105, v5
	v_pk_add_f32 v[66:67], v[122:123], v[70:71] op_sel_hi:[1,0] neg_lo:[0,1] neg_hi:[0,1]
	v_add_f32_e32 v5, v106, v5
	v_pk_mul_f32 v[108:109], v[66:67], v[66:67]
	v_add_f32_e32 v5, v107, v5
	v_pk_add_f32 v[68:69], v[124:125], v[70:71] op_sel_hi:[1,0] neg_lo:[0,1] neg_hi:[0,1]
	v_add_f32_e32 v5, v108, v5
	v_pk_mul_f32 v[110:111], v[68:69], v[68:69]
	v_add_f32_e32 v5, v109, v5
	v_add_f32_e32 v5, v110, v5
	v_add_f32_e32 v5, v111, v5
	v_mov_b32_e32 v97, s19
	s_nop 0
	v_add_f32_dpp v5, v5, v5 quad_perm:[1,0,3,2] row_mask:0xf bank_mask:0xf bound_ctrl:1
	s_nop 1
	v_add_f32_dpp v5, v5, v5 quad_perm:[2,3,0,1] row_mask:0xf bank_mask:0xf bound_ctrl:1
	s_nop 1
	v_add_f32_dpp v5, v5, v5 row_half_mirror row_mask:0xf bank_mask:0xf bound_ctrl:1
	s_nop 1
	v_add_f32_dpp v5, v5, v5 row_mirror row_mask:0xf bank_mask:0xf bound_ctrl:1
	s_nop 0
	v_readlane_b32 s24, v5, 16
	v_readlane_b32 s4, v5, 0
	v_readlane_b32 s20, v5, 32
	v_mov_b32_e32 v96, s24
	v_pk_add_f32 v[96:97], s[4:5], v[96:97]
	v_readlane_b32 s22, v5, 48
	v_pk_add_f32 v[96:97], v[96:97], s[20:21]
	s_nop 0
	v_pk_add_f32 v[96:97], v[96:97], s[22:23]
	s_nop 0
	v_pk_fma_f32 v[96:97], v[96:97], s[12:13], v[16:17] op_sel_hi:[1,0,0]
	s_nop 0
	v_mul_f32_e32 v5, 0x4b800000, v97
	v_cmp_gt_f32_e64 s[4:5], s13, v97
	s_nop 1
	v_cndmask_b32_e64 v5, v97, v5, s[4:5]
	v_rsq_f32_e32 v5, v5
	s_nop 0
	v_mul_f32_e32 v17, 0x45800000, v5
	v_cndmask_b32_e64 v98, v5, v17, s[4:5]
	v_pk_mul_f32 v[84:85], v[84:85], v[98:99] op_sel_hi:[1,0]
	v_mul_f32_e32 v5, 0x4b800000, v96
	v_pk_fma_f32 v[72:73], v[76:77], v[84:85], v[72:73]
	v_pk_mul_f32 v[76:77], v[86:87], v[98:99] op_sel_hi:[1,0]
	v_cvt_pk_bf16_f32 v72, v72, v73
	v_pk_fma_f32 v[74:75], v[78:79], v[76:77], v[74:75]
	v_pk_mul_f32 v[84:85], v[88:89], v[98:99] op_sel_hi:[1,0]
	v_cvt_pk_bf16_f32 v73, v74, v75
	global_store_dwordx2 v[52:53], v[72:73], off
	ds_read_b128 v[72:75], v140 offset:14336
	s_nop 0
	ds_read_b128 v[76:79], v140 offset:10240
	v_pk_mul_f32 v[86:87], v[90:91], v[98:99] op_sel_hi:[1,0]
	v_cmp_gt_f32_e64 s[4:5], s13, v96
	v_pk_mul_f32 v[80:81], v[80:81], v[98:99] op_sel_hi:[1,0]
	v_pk_mul_f32 v[82:83], v[82:83], v[98:99] op_sel_hi:[1,0]
	v_cndmask_b32_e64 v5, v96, v5, s[4:5]
	v_rsq_f32_e32 v5, v5
	s_waitcnt vmcnt(5) lgkmcnt(1)
; DI uint2 pk4(f32x4 v) { return make_uint2(pk2(v[0], v[1]), pk2(v[2], v[3])); }
; DI void phase10(const Params& p) {
;     ...
;             if (lane == 0) stats[row] = make_float2(mean, rstd);
; #pragma unroll
;             for (int i = 0; i < 4; ++i) {
;                 int c = i * 256 + lane * 4;
;                 float4 g = *(const float4*)(p.in[22] + c), bb = *(const float4*)(p.in[23] + c);
;                 v[rr][4 * i] = (v[rr][4 * i] - mean) * rstd * g.x + bb.x;
;                 v[rr][4 * i + 1] = (v[rr][4 * i + 1] - mean) * rstd * g.y + bb.y;
;                 v[rr][4 * i + 2] = (v[rr][4 * i + 2] - mean) * rstd * g.z + bb.z;
;                 v[rr][4 * i + 3] = (v[rr][4 * i + 3] - mean) * rstd * g.w + bb.w;
;             }
;             row_stats(v[rr], mean, rstd);
;             const float* mb = mod + (row >> 13) * 6144;
; #pragma unroll
;             for (int i = 0; i < 4; ++i) {
;                 int c = i * 256 + lane * 4;
;                 float4 sh = *(const float4*)(mb + 3072 + c), sc = *(const float4*)(mb + 4096 + c);
;                 f32x4 o;
;                 o[0] = (v[rr][4 * i] - mean) * rstd * (1.f + sc.x) + sh.x;
;                 o[1] = (v[rr][4 * i + 1] - mean) * rstd * (1.f + sc.y) + sh.y;
;                 o[2] = (v[rr][4 * i + 2] - mean) * rstd * (1.f + sc.z) + sh.z;
;                 o[3] = (v[rr][4 * i + 3] - mean) * rstd * (1.f + sc.w) + sh.w;
;                 *(uint2*)(h2 + (size_t)row * 1024 + c) = pk4(o);
	v_pk_add_f32 v[72:73], v[72:73], 1.0 op_sel_hi:[1,0]
	v_pk_add_f32 v[74:75], v[74:75], 1.0 op_sel_hi:[1,0]
	s_waitcnt vmcnt(5) lgkmcnt(0)
	v_pk_fma_f32 v[72:73], v[84:85], v[72:73], v[76:77]
	v_pk_fma_f32 v[74:75], v[86:87], v[74:75], v[78:79]
	v_cvt_pk_bf16_f32 v72, v72, v73
	v_cvt_pk_bf16_f32 v73, v74, v75
	global_store_dwordx2 v[52:53], v[72:73], off offset:512
	ds_read_b128 v[72:75], v140 offset:15360
	s_nop 0
	ds_read_b128 v[76:79], v140 offset:11264
	v_pk_mul_f32 v[84:85], v[92:93], v[98:99] op_sel_hi:[1,0]
	v_pk_mul_f32 v[86:87], v[94:95], v[98:99] op_sel_hi:[1,0]
	v_mul_f32_e32 v17, 0x45800000, v5
	s_waitcnt vmcnt(6) lgkmcnt(1)
	v_pk_add_f32 v[72:73], v[72:73], 1.0 op_sel_hi:[1,0]
	v_pk_add_f32 v[74:75], v[74:75], 1.0 op_sel_hi:[1,0]
	s_waitcnt vmcnt(6) lgkmcnt(0)
	v_pk_fma_f32 v[72:73], v[84:85], v[72:73], v[76:77]
	v_pk_fma_f32 v[74:75], v[86:87], v[74:75], v[78:79]
	v_cvt_pk_bf16_f32 v72, v72, v73
	v_cvt_pk_bf16_f32 v73, v74, v75
	global_store_dwordx2 v[52:53], v[72:73], off offset:1024
	ds_read_b128 v[72:75], v140 offset:16384
	s_nop 0
	ds_read_b128 v[76:79], v140 offset:12288
	s_waitcnt vmcnt(7) lgkmcnt(1)
	v_pk_add_f32 v[72:73], v[72:73], 1.0 op_sel_hi:[1,0]
	v_pk_add_f32 v[74:75], v[74:75], 1.0 op_sel_hi:[1,0]
	s_waitcnt vmcnt(7) lgkmcnt(0)
	v_pk_fma_f32 v[72:73], v[80:81], v[72:73], v[76:77]
	v_pk_fma_f32 v[74:75], v[82:83], v[74:75], v[78:79]
	v_cvt_pk_bf16_f32 v72, v72, v73
	v_cvt_pk_bf16_f32 v73, v74, v75
	global_store_dwordx2 v[52:53], v[72:73], off offset:1536
	v_cndmask_b32_e64 v52, v5, v17, s[4:5]
	s_and_saveexec_b64 s[4:5], vcc
	s_cbranch_execz .LBB0_996
	v_lshl_add_u64 v[50:51], v[50:51], 3, s[10:11]
	v_mov_b32_e32 v71, v52
	global_store_dwordx2 v[50:51], v[70:71], off
.LBB0_996:
	s_or_b64 exec, exec, s[4:5]
	ds_read_b128 v[70:73], v6 offset:4096
	ds_read_b128 v[74:77], v6 offset:8192
	ds_read_b128 v[78:81], v6 offset:5120
	ds_read_b128 v[82:85], v6 offset:1024
	ds_read_b128 v[86:89], v6 offset:2048
	ds_read_b128 v[90:93], v6 offset:6144
	ds_read_b128 v[94:97], v6 offset:3072
	ds_read_b128 v[98:101], v6 offset:7168
	v_lshlrev_b32_e32 v110, 16, v36
	v_and_b32_e32 v111, 0xffff0000, v36
	v_lshlrev_b32_e32 v112, 16, v37
	v_and_b32_e32 v113, 0xffff0000, v37
	v_pk_mul_f32 v[36:37], v[54:55], v[52:53] op_sel_hi:[1,0]
	v_lshlrev_b32_e32 v106, 16, v38
	v_and_b32_e32 v107, 0xffff0000, v38
	v_lshlrev_b32_e32 v108, 16, v39
	v_and_b32_e32 v109, 0xffff0000, v39
	v_pk_mul_f32 v[38:39], v[56:57], v[52:53] op_sel_hi:[1,0]
	v_lshlrev_b32_e32 v102, 16, v44
	v_and_b32_e32 v103, 0xffff0000, v44
	v_lshlrev_b32_e32 v104, 16, v45
	v_and_b32_e32 v105, 0xffff0000, v45
	v_pk_mul_f32 v[44:45], v[58:59], v[52:53] op_sel_hi:[1,0]
	v_pk_mul_f32 v[54:55], v[60:61], v[52:53] op_sel_hi:[1,0]
	v_pk_mul_f32 v[56:57], v[62:63], v[52:53] op_sel_hi:[1,0]
	v_pk_mul_f32 v[58:59], v[64:65], v[52:53] op_sel_hi:[1,0]
	v_pk_mul_f32 v[114:115], v[66:67], v[52:53] op_sel_hi:[1,0]
	ds_read_b128 v[60:63], v140 offset:9216
	ds_read_b128 v[64:67], v140 offset:13312
	v_pk_mul_f32 v[52:53], v[68:69], v[52:53] op_sel_hi:[1,0]
	v_lshlrev_b32_e32 v50, 16, v48
	v_and_b32_e32 v51, 0xffff0000, v48
	v_add_f32_e32 v5, 0, v50
	v_lshlrev_b32_e32 v48, 16, v49
	v_add_f32_e32 v5, v5, v51
	v_and_b32_e32 v49, 0xffff0000, v49
	v_add_f32_e32 v5, v5, v48
	v_add_f32_e32 v5, v5, v49
	v_add_f32_e32 v5, v5, v102
	v_add_f32_e32 v5, v5, v103
	v_add_f32_e32 v5, v5, v104
	v_add_f32_e32 v5, v5, v105
	v_add_f32_e32 v5, v5, v106
	v_add_f32_e32 v5, v5, v107
	v_add_f32_e32 v5, v5, v108
	v_add_f32_e32 v5, v5, v109
	v_add_f32_e32 v5, v5, v110
	v_add_f32_e32 v5, v5, v111
	v_add_f32_e32 v5, v5, v112
	v_add_f32_e32 v5, v5, v113
	v_lshl_add_u64 v[28:29], v[14:15], 0, v[28:29]
	s_waitcnt vmcnt(8) lgkmcnt(8)
	v_pk_fma_f32 v[68:69], v[114:115], v[70:71], v[74:75]
	v_pk_fma_f32 v[52:53], v[52:53], v[72:73], v[76:77]
	s_waitcnt vmcnt(8) lgkmcnt(6)
	v_pk_fma_f32 v[36:37], v[36:37], v[82:83], v[78:79]
	v_pk_fma_f32 v[38:39], v[38:39], v[84:85], v[80:81]
	v_add_f32_e32 v17, 0, v36
	v_add_f32_e32 v17, v17, v37
	v_add_f32_e32 v17, v17, v38
	s_waitcnt vmcnt(8) lgkmcnt(4)
	v_pk_fma_f32 v[44:45], v[44:45], v[86:87], v[90:91]
	v_add_f32_e32 v17, v17, v39
	v_add_f32_e32 v17, v17, v44
	v_pk_fma_f32 v[54:55], v[54:55], v[88:89], v[92:93]
	v_add_f32_e32 v17, v17, v45
	v_add_f32_e32 v17, v17, v54
	s_waitcnt vmcnt(8) lgkmcnt(2)
	v_pk_fma_f32 v[56:57], v[56:57], v[94:95], v[98:99]
	v_add_f32_e32 v17, v17, v55
	v_add_f32_e32 v17, v17, v56
	v_pk_fma_f32 v[58:59], v[58:59], v[96:97], v[100:101]
	v_add_f32_e32 v17, v17, v57
	v_add_f32_e32 v17, v17, v58
	v_add_f32_e32 v17, v17, v59
	v_add_f32_e32 v17, v17, v68
	v_add_f32_e32 v17, v17, v69
	v_add_f32_e32 v17, v17, v52
	v_add_f32_e32 v17, v17, v53
	v_add_f32_dpp v5, v5, v5 quad_perm:[1,0,3,2] row_mask:0xf bank_mask:0xf bound_ctrl:1
	s_waitcnt vmcnt(8) lgkmcnt(0)
; DI uint2 pk4(f32x4 v) { return make_uint2(pk2(v[0], v[1]), pk2(v[2], v[3])); }
; DI void row_stats(const float (&v)[16], float& mean, float& rstd) {
;     float s = 0.f;
; #pragma unroll
;     for (int i = 0; i < 16; ++i) s += v[i];
;     mean = wsum(s) * (1.f / 1024.f);
;     float q = 0.f;
; #pragma unroll
;     for (int i = 0; i < 16; ++i) { float d = v[i] - mean; q += d * d; }
;     rstd = rsqrtf(wsum(q) * (1.f / 1024.f) + 1e-5f);
; }
; DI void phase10(const Params& p) {
;     ...
;             row_stats(v[rr], mean, rstd);
;             const float* mb = mod + (row >> 13) * 6144;
; #pragma unroll
;             for (int i = 0; i < 4; ++i) {
;                 int c = i * 256 + lane * 4;
;                 float4 sh = *(const float4*)(mb + 3072 + c), sc = *(const float4*)(mb + 4096 + c);
;                 f32x4 o;
;                 o[0] = (v[rr][4 * i] - mean) * rstd * (1.f + sc.x) + sh.x;
;                 o[1] = (v[rr][4 * i + 1] - mean) * rstd * (1.f + sc.y) + sh.y;
;                 o[2] = (v[rr][4 * i + 2] - mean) * rstd * (1.f + sc.z) + sh.z;
;                 o[3] = (v[rr][4 * i + 3] - mean) * rstd * (1.f + sc.w) + sh.w;
;                 *(uint2*)(h2 + (size_t)row * 1024 + c) = pk4(o);
	v_pk_add_f32 v[64:65], v[64:65], 1.0 op_sel_hi:[1,0]
	v_add_f32_dpp v17, v17, v17 quad_perm:[1,0,3,2] row_mask:0xf bank_mask:0xf bound_ctrl:1
	v_add_f32_dpp v5, v5, v5 quad_perm:[2,3,0,1] row_mask:0xf bank_mask:0xf bound_ctrl:1
	v_pk_add_f32 v[66:67], v[66:67], 1.0 op_sel_hi:[1,0]
	v_add_f32_dpp v17, v17, v17 quad_perm:[2,3,0,1] row_mask:0xf bank_mask:0xf bound_ctrl:1
	v_add_f32_dpp v5, v5, v5 row_half_mirror row_mask:0xf bank_mask:0xf bound_ctrl:1
	s_nop 0
	v_add_f32_dpp v17, v17, v17 row_half_mirror row_mask:0xf bank_mask:0xf bound_ctrl:1
	v_add_f32_dpp v5, v5, v5 row_mirror row_mask:0xf bank_mask:0xf bound_ctrl:1
	s_nop 0
	v_add_f32_dpp v17, v17, v17 row_mirror row_mask:0xf bank_mask:0xf bound_ctrl:1
	s_nop 0
	v_readlane_b32 s5, v17, 16
	v_readlane_b32 s4, v17, 0
	v_readlane_b32 s19, v17, 32
	v_readlane_b32 s20, v17, 48
	v_mov_b32_e32 v17, s5
	v_add_f32_e32 v17, s4, v17
	v_add_f32_e32 v17, s19, v17
	v_add_f32_e32 v17, s20, v17
	v_mul_f32_e32 v70, 0x3a800000, v17
	v_pk_add_f32 v[72:73], v[36:37], v[70:71] op_sel_hi:[1,0] neg_lo:[0,1] neg_hi:[0,1]
	v_pk_add_f32 v[74:75], v[38:39], v[70:71] op_sel_hi:[1,0] neg_lo:[0,1] neg_hi:[0,1]
	v_pk_mul_f32 v[36:37], v[72:73], v[72:73]
	v_pk_mul_f32 v[38:39], v[74:75], v[74:75]
	v_add_f32_e32 v17, v36, v37
	v_pk_add_f32 v[76:77], v[44:45], v[70:71] op_sel_hi:[1,0] neg_lo:[0,1] neg_hi:[0,1]
	v_add_f32_e32 v17, v38, v17
	v_pk_mul_f32 v[44:45], v[76:77], v[76:77]
	v_add_f32_e32 v17, v39, v17
	v_pk_add_f32 v[78:79], v[54:55], v[70:71] op_sel_hi:[1,0] neg_lo:[0,1] neg_hi:[0,1]
	v_add_f32_e32 v17, v44, v17
	v_pk_add_f32 v[80:81], v[56:57], v[70:71] op_sel_hi:[1,0] neg_lo:[0,1] neg_hi:[0,1]
	v_pk_add_f32 v[82:83], v[58:59], v[70:71] op_sel_hi:[1,0] neg_lo:[0,1] neg_hi:[0,1]
	v_pk_add_f32 v[68:69], v[68:69], v[70:71] op_sel_hi:[1,0] neg_lo:[0,1] neg_hi:[0,1]
	v_pk_add_f32 v[70:71], v[52:53], v[70:71] op_sel_hi:[1,0] neg_lo:[0,1] neg_hi:[0,1]
	v_pk_mul_f32 v[52:53], v[78:79], v[78:79]
	v_add_f32_e32 v17, v45, v17
	v_add_f32_e32 v17, v52, v17
	v_pk_mul_f32 v[54:55], v[80:81], v[80:81]
	v_add_f32_e32 v17, v53, v17
	v_add_f32_e32 v17, v54, v17
	v_pk_mul_f32 v[56:57], v[82:83], v[82:83]
	v_add_f32_e32 v17, v55, v17
	v_add_f32_e32 v17, v56, v17
	v_pk_mul_f32 v[58:59], v[68:69], v[68:69]
	v_add_f32_e32 v17, v57, v17
	v_add_f32_e32 v17, v58, v17
	v_pk_mul_f32 v[84:85], v[70:71], v[70:71]
	v_add_f32_e32 v17, v59, v17
	v_add_f32_e32 v17, v84, v17
	v_add_f32_e32 v17, v85, v17
	v_readlane_b32 s20, v5, 16
	v_readlane_b32 s4, v5, 0
	v_add_f32_dpp v17, v17, v17 quad_perm:[1,0,3,2] row_mask:0xf bank_mask:0xf bound_ctrl:1
	s_nop 1
	v_add_f32_dpp v17, v17, v17 quad_perm:[2,3,0,1] row_mask:0xf bank_mask:0xf bound_ctrl:1
	s_nop 1
	v_add_f32_dpp v17, v17, v17 row_half_mirror row_mask:0xf bank_mask:0xf bound_ctrl:1
	s_nop 1
	v_add_f32_dpp v17, v17, v17 row_mirror row_mask:0xf bank_mask:0xf bound_ctrl:1
	s_nop 0
	v_readlane_b32 s5, v17, 0
	v_readlane_b32 s19, v17, 16
	v_readlane_b32 s21, v17, 32
	v_readlane_b32 s23, v17, 48
	v_mov_b32_e32 v17, s20
	v_add_f32_e32 v17, s4, v17
	v_readlane_b32 s4, v5, 32
	s_nop 1
	v_add_f32_e32 v17, s4, v17
	v_readlane_b32 s4, v5, 48
	s_nop 1
	v_add_f32_e32 v5, s4, v17
	v_mul_f32_e32 v58, 0x3a800000, v5
	v_pk_add_f32 v[36:37], v[50:51], v[58:59] op_sel_hi:[1,0] neg_lo:[0,1] neg_hi:[0,1]
	v_pk_add_f32 v[38:39], v[48:49], v[58:59] op_sel_hi:[1,0] neg_lo:[0,1] neg_hi:[0,1]
	v_pk_mul_f32 v[84:85], v[36:37], v[36:37]
	v_pk_mul_f32 v[86:87], v[38:39], v[38:39]
	v_add_f32_e32 v5, v84, v85
	v_pk_add_f32 v[44:45], v[102:103], v[58:59] op_sel_hi:[1,0] neg_lo:[0,1] neg_hi:[0,1]
	v_add_f32_e32 v5, v86, v5
	v_pk_mul_f32 v[88:89], v[44:45], v[44:45]
	v_add_f32_e32 v5, v87, v5
	v_pk_add_f32 v[48:49], v[104:105], v[58:59] op_sel_hi:[1,0] neg_lo:[0,1] neg_hi:[0,1]
	v_add_f32_e32 v5, v88, v5
	v_pk_mul_f32 v[90:91], v[48:49], v[48:49]
	v_add_f32_e32 v5, v89, v5
	v_pk_add_f32 v[50:51], v[106:107], v[58:59] op_sel_hi:[1,0] neg_lo:[0,1] neg_hi:[0,1]
	v_add_f32_e32 v5, v90, v5
	v_pk_mul_f32 v[92:93], v[50:51], v[50:51]
	v_add_f32_e32 v5, v91, v5
	v_pk_add_f32 v[52:53], v[108:109], v[58:59] op_sel_hi:[1,0] neg_lo:[0,1] neg_hi:[0,1]
	v_add_f32_e32 v5, v92, v5
	v_pk_mul_f32 v[94:95], v[52:53], v[52:53]
	v_add_f32_e32 v5, v93, v5
	v_pk_add_f32 v[54:55], v[110:111], v[58:59] op_sel_hi:[1,0] neg_lo:[0,1] neg_hi:[0,1]
	v_add_f32_e32 v5, v94, v5
	v_pk_mul_f32 v[96:97], v[54:55], v[54:55]
	v_add_f32_e32 v5, v95, v5
	v_pk_add_f32 v[56:57], v[112:113], v[58:59] op_sel_hi:[1,0] neg_lo:[0,1] neg_hi:[0,1]
	v_add_f32_e32 v5, v96, v5
	v_pk_mul_f32 v[98:99], v[56:57], v[56:57]
	v_add_f32_e32 v5, v97, v5
	v_add_f32_e32 v5, v98, v5
	v_add_f32_e32 v5, v99, v5
	v_mov_b32_e32 v85, s19
	s_nop 0
	v_add_f32_dpp v5, v5, v5 quad_perm:[1,0,3,2] row_mask:0xf bank_mask:0xf bound_ctrl:1
	s_nop 1
	v_add_f32_dpp v5, v5, v5 quad_perm:[2,3,0,1] row_mask:0xf bank_mask:0xf bound_ctrl:1
	s_nop 1
	v_add_f32_dpp v5, v5, v5 row_half_mirror row_mask:0xf bank_mask:0xf bound_ctrl:1
	s_nop 1
	v_add_f32_dpp v5, v5, v5 row_mirror row_mask:0xf bank_mask:0xf bound_ctrl:1
	s_nop 0
	v_readlane_b32 s24, v5, 16
	v_readlane_b32 s4, v5, 0
	v_readlane_b32 s20, v5, 32
	v_mov_b32_e32 v84, s24
	v_pk_add_f32 v[84:85], s[4:5], v[84:85]
	v_readlane_b32 s22, v5, 48
	v_pk_add_f32 v[84:85], v[84:85], s[20:21]
	s_nop 0
	v_pk_add_f32 v[84:85], v[84:85], s[22:23]
	s_nop 0
	v_pk_fma_f32 v[84:85], v[84:85], s[12:13], v[16:17] op_sel_hi:[1,0,0]
	s_nop 0
	v_mul_f32_e32 v5, 0x4b800000, v85
	v_cmp_gt_f32_e64 s[4:5], s13, v85
	s_nop 1
	v_cndmask_b32_e64 v5, v85, v5, s[4:5]
	v_rsq_f32_e32 v5, v5
	s_nop 0
	v_mul_f32_e32 v17, 0x45800000, v5
	v_cndmask_b32_e64 v86, v5, v17, s[4:5]
	v_pk_mul_f32 v[72:73], v[72:73], v[86:87] op_sel_hi:[1,0]
	v_mul_f32_e32 v5, 0x4b800000, v84
	v_pk_fma_f32 v[60:61], v[64:65], v[72:73], v[60:61]
	v_pk_mul_f32 v[64:65], v[74:75], v[86:87] op_sel_hi:[1,0]
	v_cvt_pk_bf16_f32 v60, v60, v61
	v_pk_fma_f32 v[62:63], v[66:67], v[64:65], v[62:63]
	v_pk_mul_f32 v[72:73], v[76:77], v[86:87] op_sel_hi:[1,0]
	v_cvt_pk_bf16_f32 v61, v62, v63
	global_store_dwordx2 v[28:29], v[60:61], off
	ds_read_b128 v[60:63], v140 offset:14336
	s_nop 0
	ds_read_b128 v[64:67], v140 offset:10240
	v_pk_mul_f32 v[74:75], v[78:79], v[86:87] op_sel_hi:[1,0]
	v_cmp_gt_f32_e64 s[4:5], s13, v84
	v_pk_mul_f32 v[68:69], v[68:69], v[86:87] op_sel_hi:[1,0]
	v_pk_mul_f32 v[70:71], v[70:71], v[86:87] op_sel_hi:[1,0]
	v_cndmask_b32_e64 v5, v84, v5, s[4:5]
	v_rsq_f32_e32 v5, v5
	s_waitcnt vmcnt(9) lgkmcnt(1)
; DI uint2 pk4(f32x4 v) { return make_uint2(pk2(v[0], v[1]), pk2(v[2], v[3])); }
; DI void phase10(const Params& p) {
;     ...
;             if (lane == 0) stats[row] = make_float2(mean, rstd);
;     ...
;             for (int i = 0; i < 4; ++i) {
;                 int c = i * 256 + lane * 4;
;                 float4 sh = *(const float4*)(mb + 3072 + c), sc = *(const float4*)(mb + 4096 + c);
;                 f32x4 o;
;                 o[0] = (v[rr][4 * i] - mean) * rstd * (1.f + sc.x) + sh.x;
;                 o[1] = (v[rr][4 * i + 1] - mean) * rstd * (1.f + sc.y) + sh.y;
;                 o[2] = (v[rr][4 * i + 2] - mean) * rstd * (1.f + sc.z) + sh.z;
;                 o[3] = (v[rr][4 * i + 3] - mean) * rstd * (1.f + sc.w) + sh.w;
;                 *(uint2*)(h2 + (size_t)row * 1024 + c) = pk4(o);
	v_pk_add_f32 v[60:61], v[60:61], 1.0 op_sel_hi:[1,0]
	v_pk_add_f32 v[62:63], v[62:63], 1.0 op_sel_hi:[1,0]
	s_waitcnt vmcnt(9) lgkmcnt(0)
	v_pk_fma_f32 v[60:61], v[72:73], v[60:61], v[64:65]
	v_pk_fma_f32 v[62:63], v[74:75], v[62:63], v[66:67]
	v_cvt_pk_bf16_f32 v60, v60, v61
	v_cvt_pk_bf16_f32 v61, v62, v63
	global_store_dwordx2 v[28:29], v[60:61], off offset:512
	ds_read_b128 v[60:63], v140 offset:15360
	s_nop 0
	ds_read_b128 v[64:67], v140 offset:11264
	v_pk_mul_f32 v[72:73], v[80:81], v[86:87] op_sel_hi:[1,0]
	v_pk_mul_f32 v[74:75], v[82:83], v[86:87] op_sel_hi:[1,0]
	v_mul_f32_e32 v17, 0x45800000, v5
	s_waitcnt vmcnt(10) lgkmcnt(1)
	v_pk_add_f32 v[60:61], v[60:61], 1.0 op_sel_hi:[1,0]
	v_pk_add_f32 v[62:63], v[62:63], 1.0 op_sel_hi:[1,0]
	s_waitcnt vmcnt(10) lgkmcnt(0)
	v_pk_fma_f32 v[60:61], v[72:73], v[60:61], v[64:65]
	v_pk_fma_f32 v[62:63], v[74:75], v[62:63], v[66:67]
	v_cvt_pk_bf16_f32 v60, v60, v61
	v_cvt_pk_bf16_f32 v61, v62, v63
	global_store_dwordx2 v[28:29], v[60:61], off offset:1024
	ds_read_b128 v[60:63], v140 offset:16384
	s_nop 0
	ds_read_b128 v[64:67], v140 offset:12288
	s_waitcnt vmcnt(11) lgkmcnt(1)
	v_pk_add_f32 v[60:61], v[60:61], 1.0 op_sel_hi:[1,0]
	v_pk_add_f32 v[62:63], v[62:63], 1.0 op_sel_hi:[1,0]
	s_waitcnt vmcnt(11) lgkmcnt(0)
	v_pk_fma_f32 v[60:61], v[68:69], v[60:61], v[64:65]
	v_pk_fma_f32 v[62:63], v[70:71], v[62:63], v[66:67]
	v_cvt_pk_bf16_f32 v60, v60, v61
	v_cvt_pk_bf16_f32 v61, v62, v63
	global_store_dwordx2 v[28:29], v[60:61], off offset:1536
	v_cndmask_b32_e64 v28, v5, v17, s[4:5]
	s_and_saveexec_b64 s[4:5], vcc
	s_cbranch_execz .LBB0_989
	v_lshl_add_u64 v[26:27], v[26:27], 3, s[10:11]
	v_mov_b32_e32 v59, v28
	global_store_dwordx2 v[26:27], v[58:59], off
	s_branch .LBB0_989
